# odin RoPE path: table rows of the second column block fetched before the first column block is processed (counted vmcnt wait), one exposed load latency less per RoPE tile
# baseline (speedup 1.0000x reference)
.Lodin4_rope:
	v_xor_b32_e32 v119, 16, v118
	v_lshlrev_b32_e32 v119, 2, v119
	v_and_b32_e32 v116, 16, v118
	v_cmp_eq_u32_e64 s[100:101], 0, v116
	v_and_b32_e32 v116, 15, v118
	v_lshlrev_b32_e32 v116, 3, v116
	v_lshrrev_b32_e32 v117, 5, v118
	v_lshl_add_u32 v117, v117, 9, v116
	s_sub_u32 s8, s7, 0x2000
	s_bfe_u32 s8, s8, 0x50006
	s_lshl_b32 s8, s8, 7
	s_add_u32 s8, s8, 0x3464000
	s_add_u32 s98, s90, s8
	s_addc_u32 s99, s91, 0
	global_load_dwordx2 v[120:121], v116, s[98:99]
	s_add_u32 s98, s90, 0x3464000
	s_addc_u32 s99, s91, 0
	global_load_dwordx2 v[80:81], v117, s[98:99]
	global_load_dwordx2 v[82:83], v117, s[98:99] offset:128
	global_load_dwordx2 v[84:85], v117, s[98:99] offset:256
	global_load_dwordx2 v[86:87], v117, s[98:99] offset:384
	global_load_dwordx2 v[88:89], v117, s[98:99] offset:1024
	global_load_dwordx2 v[90:91], v117, s[98:99] offset:1152
	global_load_dwordx2 v[92:93], v117, s[98:99] offset:1280
	global_load_dwordx2 v[94:95], v117, s[98:99] offset:1408
	global_load_dwordx2 v[96:97], v117, s[98:99] offset:2048
	global_load_dwordx2 v[98:99], v117, s[98:99] offset:2176
	global_load_dwordx2 v[100:101], v117, s[98:99] offset:2304
	global_load_dwordx2 v[102:103], v117, s[98:99] offset:2432
	global_load_dwordx2 v[104:105], v117, s[98:99] offset:3072
	global_load_dwordx2 v[106:107], v117, s[98:99] offset:3200
	global_load_dwordx2 v[108:109], v117, s[98:99] offset:3328
	global_load_dwordx2 v[110:111], v117, s[98:99] offset:3456
	ds_bpermute_b32 v64, v119, v48
	ds_bpermute_b32 v65, v119, v49
	ds_bpermute_b32 v66, v119, v50
	ds_bpermute_b32 v67, v119, v51
	ds_bpermute_b32 v68, v119, v52
	ds_bpermute_b32 v69, v119, v53
	ds_bpermute_b32 v70, v119, v54
	ds_bpermute_b32 v71, v119, v55
	ds_bpermute_b32 v72, v119, v56
	ds_bpermute_b32 v73, v119, v57
	ds_bpermute_b32 v74, v119, v58
	ds_bpermute_b32 v75, v119, v59
	ds_bpermute_b32 v76, v119, v60
	ds_bpermute_b32 v77, v119, v61
	ds_bpermute_b32 v78, v119, v62
	ds_bpermute_b32 v79, v119, v63
	s_waitcnt vmcnt(16) lgkmcnt(0)
	v_mul_f32_e32 v64, v121, v64
	v_mul_f32_e32 v65, v121, v65
	v_mul_f32_e32 v66, v121, v66
	v_mul_f32_e32 v67, v121, v67
	v_mul_f32_e32 v68, v121, v68
	v_mul_f32_e32 v69, v121, v69
	v_mul_f32_e32 v70, v121, v70
	v_mul_f32_e32 v71, v121, v71
	v_mul_f32_e32 v72, v121, v72
	v_mul_f32_e32 v73, v121, v73
	v_mul_f32_e32 v74, v121, v74
	v_mul_f32_e32 v75, v121, v75
	v_mul_f32_e32 v76, v121, v76
	v_mul_f32_e32 v77, v121, v77
	v_mul_f32_e32 v78, v121, v78
	v_mul_f32_e32 v79, v121, v79
	v_cndmask_b32_e64 v64, v64, -v64, s[100:101]
	v_cndmask_b32_e64 v65, v65, -v65, s[100:101]
	v_cndmask_b32_e64 v66, v66, -v66, s[100:101]
	v_cndmask_b32_e64 v67, v67, -v67, s[100:101]
	v_cndmask_b32_e64 v68, v68, -v68, s[100:101]
	v_cndmask_b32_e64 v69, v69, -v69, s[100:101]
	v_cndmask_b32_e64 v70, v70, -v70, s[100:101]
	v_cndmask_b32_e64 v71, v71, -v71, s[100:101]
	v_cndmask_b32_e64 v72, v72, -v72, s[100:101]
	v_cndmask_b32_e64 v73, v73, -v73, s[100:101]
	v_cndmask_b32_e64 v74, v74, -v74, s[100:101]
	v_cndmask_b32_e64 v75, v75, -v75, s[100:101]
	v_cndmask_b32_e64 v76, v76, -v76, s[100:101]
	v_cndmask_b32_e64 v77, v77, -v77, s[100:101]
	v_cndmask_b32_e64 v78, v78, -v78, s[100:101]
	v_cndmask_b32_e64 v79, v79, -v79, s[100:101]
	v_fma_f32 v48, v48, v120, v64
	v_fma_f32 v49, v49, v120, v65
	v_fma_f32 v50, v50, v120, v66
	v_fma_f32 v51, v51, v120, v67
	v_fma_f32 v52, v52, v120, v68
	v_fma_f32 v53, v53, v120, v69
	v_fma_f32 v54, v54, v120, v70
	v_fma_f32 v55, v55, v120, v71
	v_fma_f32 v56, v56, v120, v72
	v_fma_f32 v57, v57, v120, v73
	v_fma_f32 v58, v58, v120, v74
	v_fma_f32 v59, v59, v120, v75
	v_fma_f32 v60, v60, v120, v76
	v_fma_f32 v61, v61, v120, v77
	v_fma_f32 v62, v62, v120, v78
	v_fma_f32 v63, v63, v120, v79
	ds_bpermute_b32 v64, v119, v32
	ds_bpermute_b32 v65, v119, v33
	ds_bpermute_b32 v66, v119, v34
	ds_bpermute_b32 v67, v119, v35
	ds_bpermute_b32 v68, v119, v36
	ds_bpermute_b32 v69, v119, v37
	ds_bpermute_b32 v70, v119, v38
	ds_bpermute_b32 v71, v119, v39
	ds_bpermute_b32 v72, v119, v40
	ds_bpermute_b32 v73, v119, v41
	ds_bpermute_b32 v74, v119, v42
	ds_bpermute_b32 v75, v119, v43
	ds_bpermute_b32 v76, v119, v44
	ds_bpermute_b32 v77, v119, v45
	ds_bpermute_b32 v78, v119, v46
	ds_bpermute_b32 v79, v119, v47
	s_waitcnt lgkmcnt(0)
	v_mul_f32_e32 v64, v121, v64
	v_mul_f32_e32 v65, v121, v65
	v_mul_f32_e32 v66, v121, v66
	v_mul_f32_e32 v67, v121, v67
	v_mul_f32_e32 v68, v121, v68
	v_mul_f32_e32 v69, v121, v69
	v_mul_f32_e32 v70, v121, v70
	v_mul_f32_e32 v71, v121, v71
	v_mul_f32_e32 v72, v121, v72
	v_mul_f32_e32 v73, v121, v73
	v_mul_f32_e32 v74, v121, v74
	v_mul_f32_e32 v75, v121, v75
	v_mul_f32_e32 v76, v121, v76
	v_mul_f32_e32 v77, v121, v77
	v_mul_f32_e32 v78, v121, v78
	v_mul_f32_e32 v79, v121, v79
	v_cndmask_b32_e64 v64, v64, -v64, s[100:101]
	v_cndmask_b32_e64 v65, v65, -v65, s[100:101]
	v_cndmask_b32_e64 v66, v66, -v66, s[100:101]
	v_cndmask_b32_e64 v67, v67, -v67, s[100:101]
	v_cndmask_b32_e64 v68, v68, -v68, s[100:101]
	v_cndmask_b32_e64 v69, v69, -v69, s[100:101]
	v_cndmask_b32_e64 v70, v70, -v70, s[100:101]
	v_cndmask_b32_e64 v71, v71, -v71, s[100:101]
	v_cndmask_b32_e64 v72, v72, -v72, s[100:101]
	v_cndmask_b32_e64 v73, v73, -v73, s[100:101]
	v_cndmask_b32_e64 v74, v74, -v74, s[100:101]
	v_cndmask_b32_e64 v75, v75, -v75, s[100:101]
	v_cndmask_b32_e64 v76, v76, -v76, s[100:101]
	v_cndmask_b32_e64 v77, v77, -v77, s[100:101]
	v_cndmask_b32_e64 v78, v78, -v78, s[100:101]
	v_cndmask_b32_e64 v79, v79, -v79, s[100:101]
	v_fma_f32 v32, v32, v120, v64
	v_fma_f32 v33, v33, v120, v65
	v_fma_f32 v34, v34, v120, v66
	v_fma_f32 v35, v35, v120, v67
	v_fma_f32 v36, v36, v120, v68
	v_fma_f32 v37, v37, v120, v69
	v_fma_f32 v38, v38, v120, v70
	v_fma_f32 v39, v39, v120, v71
	v_fma_f32 v40, v40, v120, v72
	v_fma_f32 v41, v41, v120, v73
	v_fma_f32 v42, v42, v120, v74
	v_fma_f32 v43, v43, v120, v75
	v_fma_f32 v44, v44, v120, v76
	v_fma_f32 v45, v45, v120, v77
	v_fma_f32 v46, v46, v120, v78
	v_fma_f32 v47, v47, v120, v79
	ds_bpermute_b32 v64, v119, v16
	ds_bpermute_b32 v65, v119, v17
	ds_bpermute_b32 v66, v119, v18
	ds_bpermute_b32 v67, v119, v19
	ds_bpermute_b32 v68, v119, v20
	ds_bpermute_b32 v69, v119, v21
	ds_bpermute_b32 v70, v119, v22
	ds_bpermute_b32 v71, v119, v23
	ds_bpermute_b32 v72, v119, v24
	ds_bpermute_b32 v73, v119, v25
	ds_bpermute_b32 v74, v119, v26
	ds_bpermute_b32 v75, v119, v27
	ds_bpermute_b32 v76, v119, v28
	ds_bpermute_b32 v77, v119, v29
	ds_bpermute_b32 v78, v119, v30
	ds_bpermute_b32 v79, v119, v31
	s_waitcnt vmcnt(0) lgkmcnt(0)
	v_mul_f32_e32 v64, v81, v64
	v_mul_f32_e32 v65, v83, v65
	v_mul_f32_e32 v66, v85, v66
	v_mul_f32_e32 v67, v87, v67
	v_mul_f32_e32 v68, v89, v68
	v_mul_f32_e32 v69, v91, v69
	v_mul_f32_e32 v70, v93, v70
	v_mul_f32_e32 v71, v95, v71
	v_mul_f32_e32 v72, v97, v72
	v_mul_f32_e32 v73, v99, v73
	v_mul_f32_e32 v74, v101, v74
	v_mul_f32_e32 v75, v103, v75
	v_mul_f32_e32 v76, v105, v76
	v_mul_f32_e32 v77, v107, v77
	v_mul_f32_e32 v78, v109, v78
	v_mul_f32_e32 v79, v111, v79
	v_cndmask_b32_e64 v64, v64, -v64, s[100:101]
	v_cndmask_b32_e64 v65, v65, -v65, s[100:101]
	v_cndmask_b32_e64 v66, v66, -v66, s[100:101]
	v_cndmask_b32_e64 v67, v67, -v67, s[100:101]
	v_cndmask_b32_e64 v68, v68, -v68, s[100:101]
	v_cndmask_b32_e64 v69, v69, -v69, s[100:101]
	v_cndmask_b32_e64 v70, v70, -v70, s[100:101]
	v_cndmask_b32_e64 v71, v71, -v71, s[100:101]
	v_cndmask_b32_e64 v72, v72, -v72, s[100:101]
	v_cndmask_b32_e64 v73, v73, -v73, s[100:101]
	v_cndmask_b32_e64 v74, v74, -v74, s[100:101]
	v_cndmask_b32_e64 v75, v75, -v75, s[100:101]
	v_cndmask_b32_e64 v76, v76, -v76, s[100:101]
	v_cndmask_b32_e64 v77, v77, -v77, s[100:101]
	v_cndmask_b32_e64 v78, v78, -v78, s[100:101]
	v_cndmask_b32_e64 v79, v79, -v79, s[100:101]
	v_fma_f32 v16, v16, v80, v64
	v_fma_f32 v17, v17, v82, v65
	v_fma_f32 v18, v18, v84, v66
	v_fma_f32 v19, v19, v86, v67
	v_fma_f32 v20, v20, v88, v68
	v_fma_f32 v21, v21, v90, v69
	v_fma_f32 v22, v22, v92, v70
	v_fma_f32 v23, v23, v94, v71
	v_fma_f32 v24, v24, v96, v72
	v_fma_f32 v25, v25, v98, v73
	v_fma_f32 v26, v26, v100, v74
	v_fma_f32 v27, v27, v102, v75
	v_fma_f32 v28, v28, v104, v76
	v_fma_f32 v29, v29, v106, v77
	v_fma_f32 v30, v30, v108, v78
	v_fma_f32 v31, v31, v110, v79
	s_add_u32 s98, s90, 0x3465000
	s_addc_u32 s99, s91, 0
	global_load_dwordx2 v[80:81], v117, s[98:99]
	global_load_dwordx2 v[82:83], v117, s[98:99] offset:128
	global_load_dwordx2 v[84:85], v117, s[98:99] offset:256
	global_load_dwordx2 v[86:87], v117, s[98:99] offset:384
	global_load_dwordx2 v[88:89], v117, s[98:99] offset:1024
	global_load_dwordx2 v[90:91], v117, s[98:99] offset:1152
	global_load_dwordx2 v[92:93], v117, s[98:99] offset:1280
	global_load_dwordx2 v[94:95], v117, s[98:99] offset:1408
	global_load_dwordx2 v[96:97], v117, s[98:99] offset:2048
	global_load_dwordx2 v[98:99], v117, s[98:99] offset:2176
	global_load_dwordx2 v[100:101], v117, s[98:99] offset:2304
	global_load_dwordx2 v[102:103], v117, s[98:99] offset:2432
	global_load_dwordx2 v[104:105], v117, s[98:99] offset:3072
	global_load_dwordx2 v[106:107], v117, s[98:99] offset:3200
	global_load_dwordx2 v[108:109], v117, s[98:99] offset:3328
	global_load_dwordx2 v[110:111], v117, s[98:99] offset:3456
	ds_bpermute_b32 v64, v119, v0
	ds_bpermute_b32 v65, v119, v1
	ds_bpermute_b32 v66, v119, v2
	ds_bpermute_b32 v67, v119, v3
	ds_bpermute_b32 v68, v119, v4
	ds_bpermute_b32 v69, v119, v5
	ds_bpermute_b32 v70, v119, v6
	ds_bpermute_b32 v71, v119, v7
	ds_bpermute_b32 v72, v119, v8
	ds_bpermute_b32 v73, v119, v9
	ds_bpermute_b32 v74, v119, v10
	ds_bpermute_b32 v75, v119, v11
	ds_bpermute_b32 v76, v119, v12
	ds_bpermute_b32 v77, v119, v13
	ds_bpermute_b32 v78, v119, v14
	ds_bpermute_b32 v79, v119, v15
	s_waitcnt vmcnt(0) lgkmcnt(0)
	v_mul_f32_e32 v64, v81, v64
	v_mul_f32_e32 v65, v83, v65
	v_mul_f32_e32 v66, v85, v66
	v_mul_f32_e32 v67, v87, v67
	v_mul_f32_e32 v68, v89, v68
	v_mul_f32_e32 v69, v91, v69
	v_mul_f32_e32 v70, v93, v70
	v_mul_f32_e32 v71, v95, v71
	v_mul_f32_e32 v72, v97, v72
	v_mul_f32_e32 v73, v99, v73
	v_mul_f32_e32 v74, v101, v74
	v_mul_f32_e32 v75, v103, v75
	v_mul_f32_e32 v76, v105, v76
	v_mul_f32_e32 v77, v107, v77
	v_mul_f32_e32 v78, v109, v78
	v_mul_f32_e32 v79, v111, v79
	v_cndmask_b32_e64 v64, v64, -v64, s[100:101]
	v_cndmask_b32_e64 v65, v65, -v65, s[100:101]
	v_cndmask_b32_e64 v66, v66, -v66, s[100:101]
	v_cndmask_b32_e64 v67, v67, -v67, s[100:101]
	v_cndmask_b32_e64 v68, v68, -v68, s[100:101]
	v_cndmask_b32_e64 v69, v69, -v69, s[100:101]
	v_cndmask_b32_e64 v70, v70, -v70, s[100:101]
	v_cndmask_b32_e64 v71, v71, -v71, s[100:101]
	v_cndmask_b32_e64 v72, v72, -v72, s[100:101]
	v_cndmask_b32_e64 v73, v73, -v73, s[100:101]
	v_cndmask_b32_e64 v74, v74, -v74, s[100:101]
	v_cndmask_b32_e64 v75, v75, -v75, s[100:101]
	v_cndmask_b32_e64 v76, v76, -v76, s[100:101]
	v_cndmask_b32_e64 v77, v77, -v77, s[100:101]
	v_cndmask_b32_e64 v78, v78, -v78, s[100:101]
	v_cndmask_b32_e64 v79, v79, -v79, s[100:101]
	v_fma_f32 v0, v0, v80, v64
	v_fma_f32 v1, v1, v82, v65
	v_fma_f32 v2, v2, v84, v66
	v_fma_f32 v3, v3, v86, v67
	v_fma_f32 v4, v4, v88, v68
	v_fma_f32 v5, v5, v90, v69
	v_fma_f32 v6, v6, v92, v70
	v_fma_f32 v7, v7, v94, v71
	v_fma_f32 v8, v8, v96, v72
	v_fma_f32 v9, v9, v98, v73
	v_fma_f32 v10, v10, v100, v74
	v_fma_f32 v11, v11, v102, v75
	v_fma_f32 v12, v12, v104, v76
	v_fma_f32 v13, v13, v106, v77
	v_fma_f32 v14, v14, v108, v78
	v_fma_f32 v15, v15, v110, v79
	s_branch .Lodin4_norope
